# stack: + P5 per-head bias table filled with five loads and one wait (was three dependent load->wait->write rounds)
# speedup vs baseline: 1.0040x; 1.0020x over previous
; #define LAS __attribute__((address_space(3)))
; __device__ __forceinline__ void attn_wave(LAS unsigned char* wl, const bf16* Q, const bf16* K, const bf16* V, bf16* O, const float* relb, int b, int n, int h, int lane) {
;     ...
;     LAS float* biasL = (LAS float*)(wl + 6144);
;     for (int i = lane; i < 257; i += 64) biasL[i] = relb[h * 257 + i] * 1.4426950408889634f;
.LBB0_538:
	v_mbcnt_lo_u32_b32 v0, -1, 0
	v_mbcnt_hi_u32_b32 v0, -1, v0
	v_mov_b32_e32 v1, 0
	v_lshl_add_u64 v[2:3], s[48:49], 0, v[0:1]
	v_lshl_add_u64 v[2:3], v[2:3], 2, s[50:51]
	global_load_dword v4, v[2:3], off
	global_load_dword v5, v[2:3], off offset:256
	global_load_dword v6, v[2:3], off offset:512
	global_load_dword v7, v[2:3], off offset:768
	s_mov_b64 s[0:1], exec
	s_mov_b64 exec, 1
	global_load_dword v8, v[2:3], off offset:1024
	s_mov_b64 exec, s[0:1]
	v_lshl_add_u32 v9, v0, 2, s74
	s_waitcnt vmcnt(0)
	v_mul_f32_e32 v4, 0x3fb8aa3b, v4
	v_mul_f32_e32 v5, 0x3fb8aa3b, v5
	v_mul_f32_e32 v6, 0x3fb8aa3b, v6
	v_mul_f32_e32 v7, 0x3fb8aa3b, v7
	v_mul_f32_e32 v8, 0x3fb8aa3b, v8
	ds_write_b32 v9, v4
	ds_write_b32 v9, v5 offset:256
	ds_write_b32 v9, v6 offset:512
	ds_write_b32 v9, v7 offset:768
	s_mov_b64 exec, 1
	ds_write_b32 v9, v8 offset:1024
	s_mov_b64 exec, s[0:1]
